# speedup vs baseline: 1.0281x; 1.0057x over previous
; __device__ __forceinline__ void qkt8(f32x16& p0, f32x16& p1, const char* Ks, const i32x8* q8, int r32, int hi) {
;     const int s127 = 127, s124 = 124;
;     const int sw0 = (r32 >> 1) & 7, sw1 = ((32 + r32) >> 1) & 7; const char* rp0 = Ks + r32 * 128; const char* rp1 = Ks + (32 + r32) * 128;
;     ...
;     {   i32x8 ka = K8LD(rp0, 0, sw0), kb = K8LD(rp1, 0, sw1);
;         asm volatile("s_waitcnt lgkmcnt(0)" ::: "memory");
;         asm volatile("v_mfma_scale_f32_32x32x64_f8f6f4 %0, %1, %2, -4.0, %3, %4 op_sel_hi:[0,0,0]" : "=&v"(p0) : "v"(ka), "v"(q8[0]), "v"(s127), "v"(s124));
;         asm volatile("v_mfma_scale_f32_32x32x64_f8f6f4 %0, %1, %2, -4.0, %3, %4 op_sel_hi:[0,0,0]" : "=&v"(p1) : "v"(kb), "v"(q8[0]), "v"(s127), "v"(s124)); }
;     {   i32x8 ka = K8LD(rp0, 1, sw0), kb = K8LD(rp1, 1, sw1);
;         asm volatile("s_waitcnt lgkmcnt(0)" ::: "memory");
;         asm volatile("v_mfma_scale_f32_32x32x64_f8f6f4 %0, %1, %2, %0, %3, %4 op_sel_hi:[0,0,0]" : "+v"(p0) : "v"(ka), "v"(q8[1]), "v"(s127), "v"(s124));
;         asm volatile("v_mfma_scale_f32_32x32x64_f8f6f4 %0, %1, %2, %0, %3, %4 op_sel_hi:[0,0,0]" : "+v"(p1) : "v"(kb), "v"(q8[1]), "v"(s127), "v"(s124)); }
; }
; __device__ __forceinline__ void finishSM8(f32x16& p0, f32x16& p1, float& l_reg, i32x8& pa) {
;     for (int r = 0; r < 16; ++r) p1[r] = __builtin_amdgcn_exp2f(p1[r]);
;     float ps = 0; for (int r = 0; r < 16; ++r) ps += p0[r]; for (int r = 0; r < 16; ++r) ps += p1[r];
;     l_reg += ps;
; #pragma unroll
;     for (int q = 0; q < 4; ++q) { int v = 0; v = __builtin_amdgcn_cvt_pk_bf8_f32(p0[4 * q], p0[4 * q + 1], v, false); v = __builtin_amdgcn_cvt_pk_bf8_f32(p0[4 * q + 2], p0[4 * q + 3], v, true); pa[q] = v; }
; #pragma unroll
;     for (int q = 0; q < 4; ++q) { int v = 0; v = __builtin_amdgcn_cvt_pk_bf8_f32(p1[4 * q], p1[4 * q + 1], v, false); v = __builtin_amdgcn_cvt_pk_bf8_f32(p1[4 * q + 2], p1[4 * q + 3], v, true); pa[4 + q] = v; }
; }
; template <bool EXPQ>
; __device__ __forceinline__ void pv8(f32x16* o, const char* Vs, const i32x8& pa, int r32, int hi, f32x16& pe) {
;     const int s127 = 127; const char* vp = Vs + r32 * 80 + hi * 32;
;     {   const i32x8 v0 = *(const i32x8*)(vp), v1 = *(const i32x8*)(vp + 32 * 80);
;         asm volatile("s_waitcnt lgkmcnt(0)" ::: "memory");
.LBB0_1027:
	s_lshl_b32 s50, s35, 14
	v_add_u32_e32 v252, s50, v201
	v_add_u32_e32 v250, v252, v205
	v_add_u32_e32 v251, v252, v206
	ds_read_b128 v[224:227], v250 offset:49152
	ds_read_b128 v[228:231], v251 offset:49152
	ds_read_b128 v[232:235], v250 offset:53248
	ds_read_b128 v[236:239], v251 offset:53248
	v_add_u32_e32 v250, v252, v202
	v_add_u32_e32 v251, v252, v203
	ds_read_b128 v[208:211], v250 offset:49152
	ds_read_b128 v[212:215], v251 offset:49152
.Lf4_loop:
	s_mov_b32 s47, s35
	s_mov_b32 s35, s44
	s_lshl_b32 s49, s47, 14
	s_lshl_b32 s50, s44, 14
	v_add_u32_e32 v250, v252, v202
	v_add_u32_e32 v251, v252, v203
	v_add_u32_e32 v253, s50, v207
	ds_read_b128 v[216:219], v250 offset:53248
	ds_read_b128 v[220:223], v251 offset:53248
	ds_read_b128 v[136:139], v253
	ds_read_b128 v[140:143], v253 offset:16
	ds_read_b128 v[240:243], v253 offset:2560
	ds_read_b128 v[244:247], v253 offset:2576
	v_cvt_pk_bf8_f32 v128, v64, v65
	v_cvt_pk_bf8_f32 v129, v68, v69
	v_cvt_pk_bf8_f32 v130, v72, v73
	v_cvt_pk_bf8_f32 v131, v76, v77
	v_exp_f32_e32 v80, v80
	v_exp_f32_e32 v81, v81
	s_waitcnt lgkmcnt(6)
	v_mfma_scale_f32_32x32x64_f8f6f4 v[96:111], v[208:215], v[152:159], -4.0, v189, v190 op_sel_hi:[0,0,0]
	v_cvt_pk_bf8_f32 v128, v66, v67 op_sel:[0,0,1]
	v_cvt_pk_bf8_f32 v129, v70, v71 op_sel:[0,0,1]
	ds_read_b128 v[208:211], v253 offset:5120
	ds_read_b128 v[212:215], v253 offset:5136
	v_cvt_pk_bf8_f32 v130, v74, v75 op_sel:[0,0,1]
	v_cvt_pk_bf8_f32 v131, v78, v79 op_sel:[0,0,1]
	v_exp_f32_e32 v84, v84
	v_exp_f32_e32 v85, v85
	v_exp_f32_e32 v88, v88
	s_waitcnt lgkmcnt(6)
	v_mfma_scale_f32_32x32x64_f8f6f4 v[112:127], v[216:223], v[152:159], -4.0, v189, v190 op_sel_hi:[0,0,0]
	v_exp_f32_e32 v89, v89
	v_exp_f32_e32 v92, v92
	v_exp_f32_e32 v93, v93
	ds_read_b128 v[216:219], v253 offset:7680
	ds_read_b128 v[220:223], v253 offset:7696
	v_exp_f32_e32 v82, v82
	v_exp_f32_e32 v83, v83
	v_exp_f32_e32 v86, v86
	v_exp_f32_e32 v87, v87
	v_exp_f32_e32 v90, v90
	v_mfma_scale_f32_32x32x64_f8f6f4 v[96:111], v[224:231], v[144:151], v[96:111], v189, v190 op_sel_hi:[0,0,0]
	v_exp_f32_e32 v91, v91
	v_exp_f32_e32 v94, v94
	v_exp_f32_e32 v95, v95
	v_cvt_pk_bf8_f32 v132, v80, v81
	v_cvt_pk_bf8_f32 v133, v84, v85
	v_cvt_pk_bf8_f32 v134, v88, v89
	v_cvt_pk_bf8_f32 v135, v92, v93
	v_mfma_scale_f32_32x32x64_f8f6f4 v[112:127], v[232:239], v[144:151], v[112:127], v189, v190 op_sel_hi:[0,0,0]
	v_cvt_pk_bf8_f32 v132, v82, v83 op_sel:[0,0,1]
	v_cvt_pk_bf8_f32 v133, v86, v87 op_sel:[0,0,1]
	v_cvt_pk_bf8_f32 v134, v90, v91 op_sel:[0,0,1]
	v_cvt_pk_bf8_f32 v135, v94, v95 op_sel:[0,0,1]
	v_lshl_add_u64 v[186:187], s[28:29], 0, v[182:183]
	v_add_co_u32_e32 v250, vcc, s62, v186
	v_lshl_add_u64 v[184:185], s[28:29], 0, v[180:181]
	v_add_f32_e32 v248, v64, v65
	v_addc_co_u32_e32 v251, vcc, 0, v187, vcc
	v_add_co_u32_e32 v252, vcc, s63, v184
	v_add_f32_e32 v249, v80, v81
	v_add_f32_e32 v248, v66, v248
	v_addc_co_u32_e32 v253, vcc, 0, v185, vcc
	global_load_dwordx4 v[172:175], v[250:251], off
	global_load_dwordx4 v[168:171], v[252:253], off
	v_add_f32_e32 v249, v82, v249
	s_waitcnt lgkmcnt(6)
	v_mfma_f32_32x32x64_f8f6f4 v[0:15], v[128:135], v[136:143], v[0:15] cbsz:1
	s_lshl_b32 s44, s46, 14
	v_add_u32_e32 v250, s44, v199
	s_add_i32 s48, s44, 0
	v_add_u32_e32 v251, s48, v198
	v_add_u32_e32 v252, s48, v200
	s_waitcnt vmcnt(2)
	ds_write_b128 v250, v[164:167]
	ds_write_b64 v251, v[160:161] offset:49152
	ds_write_b64 v252, v[162:163] offset:49152
	v_add_f32_e32 v248, v67, v248
	v_add_f32_e32 v249, v83, v249
	v_add_f32_e32 v248, v68, v248
	v_add_f32_e32 v249, v84, v249
	v_add_f32_e32 v248, v69, v248
	v_add_f32_e32 v249, v85, v249
	v_add_f32_e32 v248, v70, v248
	v_add_f32_e32 v249, v86, v249
	v_add_f32_e32 v248, v71, v248
	v_add_f32_e32 v249, v87, v249
	v_add_f32_e32 v248, v72, v248
	v_add_f32_e32 v249, v88, v249
	s_waitcnt lgkmcnt(7)
	v_mfma_f32_32x32x64_f8f6f4 v[16:31], v[128:135], v[240:247], v[16:31] cbsz:1
	v_add_f32_e32 v248, v73, v248
	v_add_f32_e32 v249, v89, v249
	v_add_f32_e32 v248, v74, v248
	v_add_f32_e32 v249, v90, v249
	v_add_f32_e32 v248, v75, v248
	v_add_f32_e32 v249, v91, v249
	v_add_f32_e32 v248, v76, v248
	v_add_f32_e32 v249, v92, v249
	v_add_f32_e32 v248, v77, v248
	v_add_f32_e32 v249, v93, v249
	v_exp_f32_e32 v96, v96
	v_exp_f32_e32 v97, v97
	v_exp_f32_e32 v98, v98
	v_exp_f32_e32 v99, v99
	s_waitcnt lgkmcnt(0)
	s_barrier
; __device__ __forceinline__ void qkt8(f32x16& p0, f32x16& p1, const char* Ks, const i32x8* q8, int r32, int hi) {
;     const int s127 = 127, s124 = 124;
;     const int sw0 = (r32 >> 1) & 7, sw1 = ((32 + r32) >> 1) & 7; const char* rp0 = Ks + r32 * 128; const char* rp1 = Ks + (32 + r32) * 128;
;     ...
;     {   i32x8 ka = K8LD(rp0, 0, sw0), kb = K8LD(rp1, 0, sw1);
;         asm volatile("s_waitcnt lgkmcnt(0)" ::: "memory");
;         asm volatile("v_mfma_scale_f32_32x32x64_f8f6f4 %0, %1, %2, -4.0, %3, %4 op_sel_hi:[0,0,0]" : "=&v"(p0) : "v"(ka), "v"(q8[0]), "v"(s127), "v"(s124));
;         asm volatile("v_mfma_scale_f32_32x32x64_f8f6f4 %0, %1, %2, -4.0, %3, %4 op_sel_hi:[0,0,0]" : "=&v"(p1) : "v"(kb), "v"(q8[0]), "v"(s127), "v"(s124)); }
;     {   i32x8 ka = K8LD(rp0, 1, sw0), kb = K8LD(rp1, 1, sw1);
;         asm volatile("s_waitcnt lgkmcnt(0)" ::: "memory");
;         asm volatile("v_mfma_scale_f32_32x32x64_f8f6f4 %0, %1, %2, %0, %3, %4 op_sel_hi:[0,0,0]" : "+v"(p0) : "v"(ka), "v"(q8[1]), "v"(s127), "v"(s124));
;         asm volatile("v_mfma_scale_f32_32x32x64_f8f6f4 %0, %1, %2, %0, %3, %4 op_sel_hi:[0,0,0]" : "+v"(p1) : "v"(kb), "v"(q8[1]), "v"(s127), "v"(s124)); }
; }
; __device__ __forceinline__ void finishSM8(f32x16& p0, f32x16& p1, float& l_reg, i32x8& pa) {
;     for (int r = 0; r < 16; ++r) p1[r] = __builtin_amdgcn_exp2f(p1[r]);
;     float ps = 0; for (int r = 0; r < 16; ++r) ps += p0[r]; for (int r = 0; r < 16; ++r) ps += p1[r];
;     l_reg += ps;
; #pragma unroll
;     for (int q = 0; q < 4; ++q) { int v = 0; v = __builtin_amdgcn_cvt_pk_bf8_f32(p0[4 * q], p0[4 * q + 1], v, false); v = __builtin_amdgcn_cvt_pk_bf8_f32(p0[4 * q + 2], p0[4 * q + 3], v, true); pa[q] = v; }
; #pragma unroll
;     for (int q = 0; q < 4; ++q) { int v = 0; v = __builtin_amdgcn_cvt_pk_bf8_f32(p1[4 * q], p1[4 * q + 1], v, false); v = __builtin_amdgcn_cvt_pk_bf8_f32(p1[4 * q + 2], p1[4 * q + 3], v, true); pa[4 + q] = v; }
; }
; template <bool EXPQ>
; __device__ __forceinline__ void pv8(f32x16* o, const char* Vs, const i32x8& pa, int r32, int hi, f32x16& pe) {
;     const int s127 = 127; const char* vp = Vs + r32 * 80 + hi * 32;
;     {   const i32x8 v0 = *(const i32x8*)(vp), v1 = *(const i32x8*)(vp + 32 * 80);
;         asm volatile("s_waitcnt lgkmcnt(0)" ::: "memory");
	v_add_u32_e32 v252, s48, v201
	v_add_u32_e32 v250, v252, v205
	v_add_u32_e32 v251, v252, v206
	ds_read_b128 v[224:227], v250 offset:49152
	ds_read_b128 v[228:231], v251 offset:49152
	ds_read_b128 v[232:235], v250 offset:53248
	ds_read_b128 v[236:239], v251 offset:53248
	v_mfma_f32_32x32x64_f8f6f4 v[32:47], v[128:135], v[208:215], v[32:47] cbsz:1
	v_add_u32_e32 v250, v252, v202
	v_add_u32_e32 v251, v252, v203
	v_add_f32_e32 v248, v78, v248
	v_add_f32_e32 v249, v94, v249
	ds_read_b128 v[208:211], v250 offset:49152
	ds_read_b128 v[212:215], v251 offset:49152
	v_exp_f32_e32 v100, v100
	v_exp_f32_e32 v101, v101
	v_exp_f32_e32 v102, v102
	v_exp_f32_e32 v103, v103
	v_exp_f32_e32 v104, v104
	v_exp_f32_e32 v105, v105
	v_mfma_f32_32x32x64_f8f6f4 v[48:63], v[128:135], v[216:223], v[48:63] cbsz:1
	v_add_f32_e32 v248, v79, v248
	v_add_f32_e32 v249, v95, v249
	v_add_f32_e32 v178, v178, v248
	v_add_f32_e32 v178, v178, v249
	v_exp_f32_e32 v106, v106
	v_exp_f32_e32 v107, v107
	v_exp_f32_e32 v108, v108
	v_exp_f32_e32 v109, v109
	v_exp_f32_e32 v110, v110
	v_exp_f32_e32 v111, v111
	v_add_u32_e32 v250, v252, v202
	v_add_u32_e32 v251, v252, v203
	v_add_u32_e32 v253, s49, v207
	s_add_i32 s49, s50, 0
	ds_read_b128 v[216:219], v250 offset:53248
	ds_read_b128 v[220:223], v251 offset:53248
	ds_read_b128 v[136:139], v253
	ds_read_b128 v[140:143], v253 offset:16
	ds_read_b128 v[240:243], v253 offset:2560
	ds_read_b128 v[244:247], v253 offset:2576
	v_cvt_pk_bf8_f32 v128, v96, v97
	v_cvt_pk_bf8_f32 v129, v100, v101
	v_cvt_pk_bf8_f32 v130, v104, v105
	v_cvt_pk_bf8_f32 v131, v108, v109
	v_exp_f32_e32 v112, v112
	v_exp_f32_e32 v113, v113
	s_waitcnt lgkmcnt(6)
	v_mfma_scale_f32_32x32x64_f8f6f4 v[64:79], v[208:215], v[152:159], -4.0, v189, v190 op_sel_hi:[0,0,0]
	v_cvt_pk_bf8_f32 v128, v98, v99 op_sel:[0,0,1]
	v_cvt_pk_bf8_f32 v129, v102, v103 op_sel:[0,0,1]
	ds_read_b128 v[208:211], v253 offset:5120
	ds_read_b128 v[212:215], v253 offset:5136
	v_cvt_pk_bf8_f32 v130, v106, v107 op_sel:[0,0,1]
	v_cvt_pk_bf8_f32 v131, v110, v111 op_sel:[0,0,1]
	v_exp_f32_e32 v116, v116
	v_exp_f32_e32 v117, v117
	v_exp_f32_e32 v120, v120
	s_waitcnt lgkmcnt(6)
	v_mfma_scale_f32_32x32x64_f8f6f4 v[80:95], v[216:223], v[152:159], -4.0, v189, v190 op_sel_hi:[0,0,0]
	v_exp_f32_e32 v121, v121
	v_exp_f32_e32 v124, v124
	v_exp_f32_e32 v125, v125
	ds_read_b128 v[216:219], v253 offset:7680
	ds_read_b128 v[220:223], v253 offset:7696
	v_exp_f32_e32 v114, v114
	v_exp_f32_e32 v115, v115
	v_exp_f32_e32 v118, v118
	v_exp_f32_e32 v119, v119
	v_exp_f32_e32 v122, v122
	v_mfma_scale_f32_32x32x64_f8f6f4 v[64:79], v[224:231], v[144:151], v[64:79], v189, v190 op_sel_hi:[0,0,0]
	v_exp_f32_e32 v123, v123
	v_exp_f32_e32 v126, v126
	v_exp_f32_e32 v127, v127
	v_cvt_pk_bf8_f32 v132, v112, v113
	v_cvt_pk_bf8_f32 v133, v116, v117
	v_cvt_pk_bf8_f32 v134, v120, v121
	v_cvt_pk_bf8_f32 v135, v124, v125
	v_mfma_scale_f32_32x32x64_f8f6f4 v[80:95], v[232:239], v[144:151], v[80:95], v189, v190 op_sel_hi:[0,0,0]
	v_cvt_pk_bf8_f32 v132, v114, v115 op_sel:[0,0,1]
	v_cvt_pk_bf8_f32 v133, v118, v119 op_sel:[0,0,1]
	v_cvt_pk_bf8_f32 v134, v122, v123 op_sel:[0,0,1]
	v_cvt_pk_bf8_f32 v135, v126, v127 op_sel:[0,0,1]
	s_cmp_ge_u32 s3, s69
	s_cselect_b64 s[44:45], -1, 0
	s_and_b64 vcc, exec, s[44:45]
	s_cbranch_vccnz .Lf4_skip
	v_add_co_u32_e32 v160, vcc, 0x49730000, v186
	v_add_f32_e32 v248, v96, v97
	v_add_f32_e32 v249, v112, v113
	v_addc_co_u32_e32 v161, vcc, 0, v187, vcc
	v_add_co_u32_e32 v162, vcc, 0x48b30000, v184
	v_add_f32_e32 v248, v98, v248
	v_add_f32_e32 v249, v114, v249
	v_addc_co_u32_e32 v163, vcc, 0, v185, vcc
	global_load_dwordx4 v[164:167], v[160:161], off
	s_nop 0
	global_load_dwordx4 v[160:163], v[162:163], off
	s_branch .Lf4_sedone

; #define SBAR() __builtin_amdgcn_sched_barrier(0)
; #define SWAIT() do { if constexpr (FIXED) asm volatile("s_waitcnt vmcnt(2)" ::: "memory"); else if constexpr (SD == 2) asm volatile("s_waitcnt vmcnt(4)" ::: "memory"); else asm volatile("s_waitcnt vmcnt(0)" ::: "memory"); } while (0)
; #define PVX(VOFF, PE) do { if constexpr (FIXED) pv8<true>(o, (const char*)V_lds + (VOFF), pa8, r32, hi, PE); else pv_d0(o, vb0 + (VOFF), pa0, pa1, pa2, pa3); } while (0)
; #define PSMG(P0, P1, MN, AL) do { if constexpr (!FIXED) partialSM(P0, P1, m_reg, MN, AL); } while (0)
; #define RESCX(a) do { if constexpr (!FIXED) RESC(a); } while (0)
; template <bool EXPQ>
; __device__ __forceinline__ void pv8(f32x16* o, const char* Vs, const i32x8& pa, int r32, int hi, f32x16& pe) {
;     const int s127 = 127; const char* vp = Vs + r32 * 80 + hi * 32;
;     {   const i32x8 v0 = *(const i32x8*)(vp), v1 = *(const i32x8*)(vp + 32 * 80);
;         asm volatile("s_waitcnt lgkmcnt(0)" ::: "memory");
;         asm volatile("v_mfma_scale_f32_32x32x64_f8f6f4 %0, %1, %2, %0, %3, %3 op_sel_hi:[0,0,0] cbsz:1" : "+v"(o[0]) : "v"(pa), "v"(v0), "v"(s127));
;         asm volatile("v_mfma_scale_f32_32x32x64_f8f6f4 %0, %1, %2, %0, %3, %3 op_sel_hi:[0,0,0] cbsz:1" : "+v"(o[1]) : "v"(pa), "v"(v1), "v"(s127)); }
;     {   const i32x8 v2 = *(const i32x8*)(vp + 64 * 80), v3 = *(const i32x8*)(vp + 96 * 80);
;         if constexpr (EXPQ) { for (int r = 0; r < 16; ++r) pe[r] = __builtin_amdgcn_exp2f(pe[r]); asm volatile("" : "+v"(pe)); }
;         asm volatile("s_waitcnt lgkmcnt(0)" ::: "memory");
;         asm volatile("v_mfma_scale_f32_32x32x64_f8f6f4 %0, %1, %2, %0, %3, %3 op_sel_hi:[0,0,0] cbsz:1" : "+v"(o[2]) : "v"(pa), "v"(v2), "v"(s127));
;         asm volatile("v_mfma_scale_f32_32x32x64_f8f6f4 %0, %1, %2, %0, %3, %3 op_sel_hi:[0,0,0] cbsz:1" : "+v"(o[3]) : "v"(pa), "v"(v3), "v"(s127)); }
; }
; template <bool FIXED> ...
;     ...
;         if (SD == 1 || j + 3 < NT) SLOAD(SE, (j + 1 + SD) * KVBLK); SBAR();
;         PVX(bp * (int)SHM_V, pA0); PSMG(pA0, pA1, mnA, alA);
;         SWAIT(); SWRITE(bn, SO);
;         RESCX(alA); __syncthreads();
;         { const int t_ = bp; bp = bc; bc = bn; bn = t_; }
;     }
.Lf4_sedone:
	s_waitcnt lgkmcnt(6)
	v_mfma_f32_32x32x64_f8f6f4 v[0:15], v[128:135], v[136:143], v[0:15] cbsz:1
	v_add_u32_e32 v250, s50, v199
	v_add_u32_e32 v251, s49, v198
	v_add_u32_e32 v252, s49, v200
	s_and_b64 vcc, exec, s[44:45]
	s_cbranch_vccnz .Lf4_lastw
	s_waitcnt vmcnt(2)
.Lf4_wr:
	ds_write_b128 v250, v[172:175]
	ds_write_b64 v251, v[168:169] offset:49152
	ds_write_b64 v252, v[170:171] offset:49152
	v_add_f32_e32 v248, v99, v248
	v_add_f32_e32 v249, v115, v249
	v_add_f32_e32 v248, v100, v248
	v_add_f32_e32 v249, v116, v249
	v_add_f32_e32 v248, v101, v248
	v_add_f32_e32 v249, v117, v249
	v_add_f32_e32 v248, v102, v248
	v_add_f32_e32 v249, v118, v249
	v_add_f32_e32 v248, v103, v248
	v_add_f32_e32 v249, v119, v249
	v_add_f32_e32 v248, v104, v248
	v_add_f32_e32 v249, v120, v249
	s_waitcnt lgkmcnt(7)
	v_mfma_f32_32x32x64_f8f6f4 v[16:31], v[128:135], v[240:247], v[16:31] cbsz:1
	v_add_f32_e32 v248, v105, v248
	v_add_f32_e32 v249, v121, v249
	v_add_f32_e32 v248, v106, v248
	v_add_f32_e32 v249, v122, v249
	v_add_f32_e32 v248, v107, v248
	v_add_f32_e32 v249, v123, v249
	v_add_f32_e32 v248, v108, v248
	v_add_f32_e32 v249, v124, v249
	v_add_f32_e32 v248, v109, v248
	v_add_f32_e32 v249, v125, v249
	v_exp_f32_e32 v64, v64
	v_exp_f32_e32 v65, v65
	v_exp_f32_e32 v66, v66
	v_exp_f32_e32 v67, v67
	s_waitcnt lgkmcnt(0)
	s_barrier
	s_lshl_b32 s50, s35, 14
	v_add_u32_e32 v252, s50, v201
	v_add_u32_e32 v250, v252, v205
	v_add_u32_e32 v251, v252, v206
	ds_read_b128 v[224:227], v250 offset:49152
	ds_read_b128 v[228:231], v251 offset:49152
	ds_read_b128 v[232:235], v250 offset:53248
	ds_read_b128 v[236:239], v251 offset:53248
	v_mfma_f32_32x32x64_f8f6f4 v[32:47], v[128:135], v[208:215], v[32:47] cbsz:1
	v_add_u32_e32 v250, v252, v202
	v_add_u32_e32 v251, v252, v203
	v_add_f32_e32 v248, v110, v248
	v_add_f32_e32 v249, v126, v249
	ds_read_b128 v[208:211], v250 offset:49152
	ds_read_b128 v[212:215], v251 offset:49152
	v_exp_f32_e32 v68, v68
	v_exp_f32_e32 v69, v69
	v_exp_f32_e32 v70, v70
	v_exp_f32_e32 v71, v71
	v_exp_f32_e32 v72, v72
	v_exp_f32_e32 v73, v73
	v_mfma_f32_32x32x64_f8f6f4 v[48:63], v[128:135], v[216:223], v[48:63] cbsz:1
	v_add_f32_e32 v248, v111, v248
	v_add_f32_e32 v249, v127, v249
	v_add_f32_e32 v178, v178, v248
	v_add_f32_e32 v178, v178, v249
	v_exp_f32_e32 v74, v74
	v_exp_f32_e32 v75, v75
	v_exp_f32_e32 v76, v76
	v_exp_f32_e32 v77, v77
	v_exp_f32_e32 v78, v78
	v_exp_f32_e32 v79, v79
	v_lshl_add_u64 v[180:181], v[180:181], 0, s[22:23]
	v_lshl_add_u64 v[182:183], v[182:183], 0, s[22:23]
	s_add_i32 s3, s3, 2
	s_and_b64 vcc, exec, s[44:45]
	s_cbranch_vccnz .LBB0_1031
	s_mov_b32 s44, s46
	s_mov_b32 s46, s47
	s_branch .Lf4_loop
